# speedup vs baseline: 1.0417x; 1.0066x over previous
.LBB0_9:
	s_or_b64 exec, exec, s[10:11]
	flat_load_dwordx2 v[34:35], v[4:5] offset:160
	v_lshl_add_u64 v[42:43], v[20:21], 0, v[6:7]
	v_lshl_add_u64 v[46:47], v[20:21], 0, v[10:11]
	v_lshl_add_u64 v[50:51], v[20:21], 0, v[12:13]
	v_lshl_add_u64 v[54:55], v[20:21], 0, v[14:15]
	v_lshl_add_u64 v[64:65], v[20:21], 0, v[16:17]
	flat_load_dwordx4 v[30:33], v[42:43] nt
	flat_load_dwordx4 v[66:69], v[42:43] offset:1024 nt
	flat_load_dwordx4 v[70:73], v[42:43] offset:2048 nt
	flat_load_dwordx4 v[74:77], v[42:43] offset:3072 nt
	flat_load_dwordx4 v[78:81], v[46:47] nt
	flat_load_dwordx4 v[82:85], v[50:51] nt
	flat_load_dwordx4 v[86:89], v[54:55] nt
	flat_load_dwordx4 v[90:93], v[64:65] nt
	v_lshlrev_b64 v[36:37], 12, v[18:19]
	s_waitcnt vmcnt(0) lgkmcnt(0)
	v_mov_b32_e32 v98, v34
	v_mov_b32_e32 v99, v35
	v_lshl_add_u64 v[34:35], v[34:35], 0, v[36:37]
	v_lshl_add_u64 v[62:63], v[34:35], 0, v[8:9]
	v_cvt_pk_bf16_f32 v94, v30, v31
	v_cvt_pk_bf16_f32 v95, v32, v33
	flat_store_dwordx2 v[62:63], v[94:95]
	v_cvt_pk_bf16_f32 v96, v66, v67
	v_cvt_pk_bf16_f32 v97, v68, v69
	flat_store_dwordx2 v[62:63], v[96:97] offset:512
	v_cvt_pk_bf16_f32 v94, v70, v71
	v_cvt_pk_bf16_f32 v95, v72, v73
	flat_store_dwordx2 v[62:63], v[94:95] offset:1024
	v_cvt_pk_bf16_f32 v96, v74, v75
	v_cvt_pk_bf16_f32 v97, v76, v77
	flat_store_dwordx2 v[62:63], v[96:97] offset:1536
	v_cvt_pk_bf16_f32 v94, v78, v79
	v_cvt_pk_bf16_f32 v95, v80, v81
	flat_store_dwordx2 v[62:63], v[94:95] offset:2048
	v_cvt_pk_bf16_f32 v96, v82, v83
	v_cvt_pk_bf16_f32 v97, v84, v85
	flat_store_dwordx2 v[62:63], v[96:97] offset:2560
	v_cvt_pk_bf16_f32 v94, v86, v87
	v_cvt_pk_bf16_f32 v95, v88, v89
	flat_store_dwordx2 v[62:63], v[94:95] offset:3072
	v_cvt_pk_bf16_f32 v96, v90, v91
	v_cvt_pk_bf16_f32 v97, v92, v93
	flat_store_dwordx2 v[62:63], v[96:97] offset:3584
	v_mul_f32_e32 v20, v31, v31
	v_mul_f32_e32 v21, v67, v67
	v_fmac_f32_e32 v20, v30, v30
	v_fmac_f32_e32 v21, v66, v66
	v_fmac_f32_e32 v20, v32, v32
	v_fmac_f32_e32 v21, v68, v68
	v_fmac_f32_e32 v20, v33, v33
	v_fmac_f32_e32 v21, v69, v69
	v_add_f32_e32 v20, v20, v21
	v_mul_f32_e32 v21, v71, v71
	v_fmac_f32_e32 v21, v70, v70
	v_fmac_f32_e32 v21, v72, v72
	v_fmac_f32_e32 v21, v73, v73
	v_add_f32_e32 v20, v20, v21
	v_mul_f32_e32 v21, v75, v75
	v_fmac_f32_e32 v21, v74, v74
	v_fmac_f32_e32 v21, v76, v76
	v_fmac_f32_e32 v21, v77, v77
	v_add_f32_e32 v20, v20, v21
	v_mul_f32_e32 v21, v79, v79
	v_fmac_f32_e32 v21, v78, v78
	v_fmac_f32_e32 v21, v80, v80
	v_fmac_f32_e32 v21, v81, v81
	v_add_f32_e32 v20, v20, v21
	v_mul_f32_e32 v21, v83, v83
	v_fmac_f32_e32 v21, v82, v82
	v_fmac_f32_e32 v21, v84, v84
	v_fmac_f32_e32 v21, v85, v85
	v_add_f32_e32 v20, v20, v21
	v_mul_f32_e32 v21, v87, v87
	v_fmac_f32_e32 v21, v86, v86
	v_fmac_f32_e32 v21, v88, v88
	v_fmac_f32_e32 v21, v89, v89
	v_add_f32_e32 v20, v20, v21
	v_mul_f32_e32 v21, v91, v91
	v_fmac_f32_e32 v21, v90, v90
	v_fmac_f32_e32 v21, v92, v92
	v_fmac_f32_e32 v21, v93, v93
	v_add_f32_e32 v20, v20, v21
	ds_bpermute_b32 v21, v22, v20
	s_waitcnt lgkmcnt(0)
	v_add_f32_e32 v20, v20, v21
	ds_bpermute_b32 v21, v23, v20
	s_waitcnt lgkmcnt(0)
	v_add_f32_e32 v20, v20, v21
	ds_bpermute_b32 v21, v24, v20
	s_waitcnt lgkmcnt(0)
	v_add_f32_e32 v20, v20, v21
	ds_bpermute_b32 v21, v26, v20
	s_waitcnt lgkmcnt(0)
	v_add_f32_e32 v20, v20, v21
	ds_bpermute_b32 v21, v27, v20
	s_waitcnt lgkmcnt(0)
	v_add_f32_e32 v20, v20, v21
	ds_bpermute_b32 v21, v28, v20
	s_and_saveexec_b64 s[10:11], s[4:5]
	s_cbranch_execz .LBB0_4
	s_waitcnt lgkmcnt(0)
	v_add_f32_e32 v20, v20, v21
	v_fma_f32 v20, v20, s14, 0.5
	v_trunc_f32_e32 v20, v20
	v_mul_f32_e32 v21, 0x2f800000, v20
	v_floor_f32_e32 v21, v21
	v_fmac_f32_e32 v20, 0xcf800000, v21
	v_cvt_u32_f32_e32 v21, v21
	v_cvt_u32_f32_e32 v20, v20
	v_lshl_add_u64 v[18:19], v[18:19], 3, v[98:99]
	v_add_co_u32_e32 v18, vcc, 0x8010000, v18
	s_nop 1
	v_addc_co_u32_e32 v19, vcc, 0, v19, vcc
	flat_store_dwordx2 v[18:19], v[20:21]
	s_branch .LBB0_4

.LBB0_824:
	s_mov_b32 s0, 0x8000
	v_mov_b64_e32 v[0:1], s[78:79]
	s_waitcnt vmcnt(0)
	flat_load_dwordx2 v[2:3], v[0:1] offset:160
	v_ashrrev_i32_e32 v0, 6, v204
	s_nop 0
	v_lshl_add_u32 v0, s80, 3, v0
	v_cmp_gt_i32_e32 vcc, s0, v0
	s_and_saveexec_b64 s[0:1], vcc
	s_cbranch_execz .LBB0_827
	v_lshlrev_b32_e32 v1, 2, v204
	s_mov_b64 s[0:1], 0x8214000
	v_and_b32_e32 v8, 0xfc, v1
	s_waitcnt vmcnt(0) lgkmcnt(0)
	v_lshl_add_u64 v[2:3], v[2:3], 0, s[0:1]
	v_readlane_b32 s0, v255, 0
	v_mov_b32_e32 v5, 0
	v_or_b32_e32 v10, 0x400, v8
	v_or_b32_e32 v12, 0x500, v8
	v_or_b32_e32 v14, 0x600, v8
	v_or_b32_e32 v16, 0x700, v8
	s_lshl_b32 s2, s0, 3
	s_mov_b64 s[0:1], 0
	v_mov_b32_e32 v18, 0x358637bd
	s_mov_b32 s3, 0x800000
	v_mov_b64_e32 v[6:7], s[78:79]
	v_lshlrev_b32_e32 v4, 1, v8
	v_lshlrev_b32_e32 v8, 2, v8
	v_mov_b32_e32 v9, v5
	v_lshlrev_b32_e32 v10, 2, v10
	v_mov_b32_e32 v11, v5
	v_lshlrev_b32_e32 v12, 2, v12
	v_mov_b32_e32 v13, v5
	v_lshlrev_b32_e32 v14, 2, v14
	v_mov_b32_e32 v15, v5
	v_lshlrev_b32_e32 v16, 2, v16
	v_mov_b32_e32 v17, v5
	s_movk_i32 s4, 0x7fff
	global_load_dwordx4 v[40:43], v[6:7], off offset:144
	global_load_dwordx2 v[44:45], v[6:7], off offset:160
	s_waitcnt vmcnt(0)
	v_lshl_add_u64 v[46:47], v[40:41], 0, v[8:9]
	v_add_co_u32_e32 v46, vcc, 0x1000, v46
	s_nop 1
	v_addc_co_u32_e32 v47, vcc, 0, v47, vcc
	global_load_dwordx4 v[48:51], v[46:47], off offset:-4096
	global_load_dwordx4 v[52:55], v[46:47], off offset:-3072
	global_load_dwordx4 v[56:59], v[46:47], off offset:-2048
	global_load_dwordx4 v[60:63], v[46:47], off offset:-1024
	global_load_dwordx4 v[64:67], v[46:47], off
	global_load_dwordx4 v[68:71], v[46:47], off offset:1024
	global_load_dwordx4 v[72:75], v[46:47], off offset:2048
	global_load_dwordx4 v[76:79], v[46:47], off offset:3072
	v_lshl_add_u64 v[118:119], v[42:43], 0, v[8:9]
	v_add_co_u32_e32 v118, vcc, 0x1000, v118
	s_nop 1
	v_addc_co_u32_e32 v119, vcc, 0, v119, vcc
	v_lshl_add_u64 v[120:121], v[44:45], 0, v[4:5]
.Lfin_loop:
	v_ashrrev_i32_e32 v1, 31, v0
	v_lshl_add_u64 v[26:27], v[0:1], 3, v[2:3]
	global_load_dwordx2 v[26:27], v[26:27], off
	v_lshlrev_b64 v[28:29], 12, v[0:1]
	v_lshl_add_u64 v[28:29], v[120:121], 0, v[28:29]
	global_load_dwordx2 v[80:81], v[28:29], off nt
	global_load_dwordx2 v[82:83], v[28:29], off offset:512 nt
	global_load_dwordx2 v[84:85], v[28:29], off offset:1024 nt
	global_load_dwordx2 v[86:87], v[28:29], off offset:1536 nt
	global_load_dwordx2 v[88:89], v[28:29], off offset:2048 nt
	global_load_dwordx2 v[90:91], v[28:29], off offset:2560 nt
	global_load_dwordx2 v[92:93], v[28:29], off offset:3072 nt
	global_load_dwordx2 v[94:95], v[28:29], off offset:3584 nt
	v_lshlrev_b64 v[30:31], 13, v[0:1]
	v_lshl_add_u64 v[30:31], v[118:119], 0, v[30:31]
	v_add_u32_e32 v0, s2, v0
	v_cmp_lt_i32_e32 vcc, s4, v0
	s_or_b64 s[0:1], vcc, s[0:1]
	s_waitcnt vmcnt(0)
	v_ffbh_u32_e32 v19, v27
	v_min_u32_e32 v19, 32, v19
	v_lshlrev_b64 v[26:27], v19, v[26:27]
	v_min_u32_e32 v26, 1, v26
	v_or_b32_e32 v26, v27, v26
	v_cvt_f32_u32_e32 v26, v26
	v_sub_u32_e32 v19, 32, v19
	v_ldexp_f32 v19, v26, v19
	v_fmamk_f32 v19, v19, 0x30000000, v18
	v_mul_f32_e32 v26, 0x4b800000, v19
	v_cmp_gt_f32_e32 vcc, s3, v19
	s_nop 1
	v_cndmask_b32_e32 v19, v19, v26, vcc
	v_rsq_f32_e32 v19, v19
	s_nop 0
	v_mul_f32_e32 v1, 0x45800000, v19
	v_cndmask_b32_e32 v34, v19, v1, vcc
	v_lshlrev_b32_e32 v20, 16, v80
	v_and_b32_e32 v21, 0xffff0000, v80
	v_lshlrev_b32_e32 v22, 16, v81
	v_and_b32_e32 v23, 0xffff0000, v81
	v_pk_mul_f32 v[20:21], v[34:35], v[20:21] op_sel_hi:[0,1]
	v_pk_mul_f32 v[22:23], v[34:35], v[22:23] op_sel_hi:[0,1]
	v_pk_mul_f32 v[20:21], v[48:49], v[20:21]
	v_pk_mul_f32 v[22:23], v[50:51], v[22:23]
	global_store_dwordx4 v[30:31], v[20:23], off offset:-4096 nt
	v_lshlrev_b32_e32 v36, 16, v82
	v_and_b32_e32 v37, 0xffff0000, v82
	v_lshlrev_b32_e32 v38, 16, v83
	v_and_b32_e32 v39, 0xffff0000, v83
	v_pk_mul_f32 v[36:37], v[34:35], v[36:37] op_sel_hi:[0,1]
	v_pk_mul_f32 v[38:39], v[34:35], v[38:39] op_sel_hi:[0,1]
	v_pk_mul_f32 v[36:37], v[52:53], v[36:37]
	v_pk_mul_f32 v[38:39], v[54:55], v[38:39]
	global_store_dwordx4 v[30:31], v[36:39], off offset:-3072 nt
	v_lshlrev_b32_e32 v20, 16, v84
	v_and_b32_e32 v21, 0xffff0000, v84
	v_lshlrev_b32_e32 v22, 16, v85
	v_and_b32_e32 v23, 0xffff0000, v85
	v_pk_mul_f32 v[20:21], v[34:35], v[20:21] op_sel_hi:[0,1]
	v_pk_mul_f32 v[22:23], v[34:35], v[22:23] op_sel_hi:[0,1]
	v_pk_mul_f32 v[20:21], v[56:57], v[20:21]
	v_pk_mul_f32 v[22:23], v[58:59], v[22:23]
	global_store_dwordx4 v[30:31], v[20:23], off offset:-2048 nt
	v_lshlrev_b32_e32 v36, 16, v86
	v_and_b32_e32 v37, 0xffff0000, v86
	v_lshlrev_b32_e32 v38, 16, v87
	v_and_b32_e32 v39, 0xffff0000, v87
	v_pk_mul_f32 v[36:37], v[34:35], v[36:37] op_sel_hi:[0,1]
	v_pk_mul_f32 v[38:39], v[34:35], v[38:39] op_sel_hi:[0,1]
	v_pk_mul_f32 v[36:37], v[60:61], v[36:37]
	v_pk_mul_f32 v[38:39], v[62:63], v[38:39]
	global_store_dwordx4 v[30:31], v[36:39], off offset:-1024 nt
	v_lshlrev_b32_e32 v20, 16, v88
	v_and_b32_e32 v21, 0xffff0000, v88
	v_lshlrev_b32_e32 v22, 16, v89
	v_and_b32_e32 v23, 0xffff0000, v89
	v_pk_mul_f32 v[20:21], v[34:35], v[20:21] op_sel_hi:[0,1]
	v_pk_mul_f32 v[22:23], v[34:35], v[22:23] op_sel_hi:[0,1]
	v_pk_mul_f32 v[20:21], v[64:65], v[20:21]
	v_pk_mul_f32 v[22:23], v[66:67], v[22:23]
	global_store_dwordx4 v[30:31], v[20:23], off nt
	v_lshlrev_b32_e32 v36, 16, v90
	v_and_b32_e32 v37, 0xffff0000, v90
	v_lshlrev_b32_e32 v38, 16, v91
	v_and_b32_e32 v39, 0xffff0000, v91
	v_pk_mul_f32 v[36:37], v[34:35], v[36:37] op_sel_hi:[0,1]
	v_pk_mul_f32 v[38:39], v[34:35], v[38:39] op_sel_hi:[0,1]
	v_pk_mul_f32 v[36:37], v[68:69], v[36:37]
	v_pk_mul_f32 v[38:39], v[70:71], v[38:39]
	global_store_dwordx4 v[30:31], v[36:39], off offset:1024 nt
	v_lshlrev_b32_e32 v20, 16, v92
	v_and_b32_e32 v21, 0xffff0000, v92
	v_lshlrev_b32_e32 v22, 16, v93
	v_and_b32_e32 v23, 0xffff0000, v93
	v_pk_mul_f32 v[20:21], v[34:35], v[20:21] op_sel_hi:[0,1]
	v_pk_mul_f32 v[22:23], v[34:35], v[22:23] op_sel_hi:[0,1]
	v_pk_mul_f32 v[20:21], v[72:73], v[20:21]
	v_pk_mul_f32 v[22:23], v[74:75], v[22:23]
	global_store_dwordx4 v[30:31], v[20:23], off offset:2048 nt
	v_lshlrev_b32_e32 v36, 16, v94
	v_and_b32_e32 v37, 0xffff0000, v94
	v_lshlrev_b32_e32 v38, 16, v95
	v_and_b32_e32 v39, 0xffff0000, v95
	v_pk_mul_f32 v[36:37], v[34:35], v[36:37] op_sel_hi:[0,1]
	v_pk_mul_f32 v[38:39], v[34:35], v[38:39] op_sel_hi:[0,1]
	v_pk_mul_f32 v[36:37], v[76:77], v[36:37]
	v_pk_mul_f32 v[38:39], v[78:79], v[38:39]
	global_store_dwordx4 v[30:31], v[36:39], off offset:3072 nt
	s_andn2_b64 exec, exec, s[0:1]
	s_cbranch_execnz .Lfin_loop
